# v8 + P0 cache-K f32->bf16 loop with 8 iterations of loads in flight (counted vmcnt)
# baseline (speedup 1.0000x reference)
.LBB0_139:
	s_mul_i32 s31, s54, 7
	s_add_i32 s31, s31, s3
	s_cmpk_lt_i32 s31, 0x4000
	s_cbranch_scc0 .Lkc_tail
	global_load_dwordx4 v[12:15], v[2:3], off offset:-16
	global_load_dwordx4 v[16:19], v[2:3], off
	v_lshl_add_u64 v[2:3], v[2:3], 0, s[0:1]
	global_load_dwordx4 v[20:23], v[2:3], off offset:-16
	global_load_dwordx4 v[24:27], v[2:3], off
	v_lshl_add_u64 v[2:3], v[2:3], 0, s[0:1]
	global_load_dwordx4 v[28:31], v[2:3], off offset:-16
	global_load_dwordx4 v[32:35], v[2:3], off
	v_lshl_add_u64 v[2:3], v[2:3], 0, s[0:1]
	global_load_dwordx4 v[36:39], v[2:3], off offset:-16
	global_load_dwordx4 v[40:43], v[2:3], off
	v_lshl_add_u64 v[2:3], v[2:3], 0, s[0:1]
	global_load_dwordx4 v[44:47], v[2:3], off offset:-16
	global_load_dwordx4 v[48:51], v[2:3], off
	v_lshl_add_u64 v[2:3], v[2:3], 0, s[0:1]
	global_load_dwordx4 v[52:55], v[2:3], off offset:-16
	global_load_dwordx4 v[56:59], v[2:3], off
	v_lshl_add_u64 v[2:3], v[2:3], 0, s[0:1]
	global_load_dwordx4 v[60:63], v[2:3], off offset:-16
	global_load_dwordx4 v[64:67], v[2:3], off
	v_lshl_add_u64 v[2:3], v[2:3], 0, s[0:1]
	global_load_dwordx4 v[68:71], v[2:3], off offset:-16
	global_load_dwordx4 v[72:75], v[2:3], off
	v_lshl_add_u64 v[2:3], v[2:3], 0, s[0:1]
	s_waitcnt vmcnt(14)
	v_cvt_pk_bf16_f32 v12, v12, v13
	v_cvt_pk_bf16_f32 v13, v14, v15
	v_cvt_pk_bf16_f32 v14, v16, v17
	v_cvt_pk_bf16_f32 v15, v18, v19
	global_store_dwordx4 v[0:1], v[12:15], off
	v_lshl_add_u64 v[0:1], v[0:1], 0, s[8:9]
	s_waitcnt vmcnt(13)
	v_cvt_pk_bf16_f32 v20, v20, v21
	v_cvt_pk_bf16_f32 v21, v22, v23
	v_cvt_pk_bf16_f32 v22, v24, v25
	v_cvt_pk_bf16_f32 v23, v26, v27
	global_store_dwordx4 v[0:1], v[20:23], off
	v_lshl_add_u64 v[0:1], v[0:1], 0, s[8:9]
	s_waitcnt vmcnt(12)
	v_cvt_pk_bf16_f32 v28, v28, v29
	v_cvt_pk_bf16_f32 v29, v30, v31
	v_cvt_pk_bf16_f32 v30, v32, v33
	v_cvt_pk_bf16_f32 v31, v34, v35
	global_store_dwordx4 v[0:1], v[28:31], off
	v_lshl_add_u64 v[0:1], v[0:1], 0, s[8:9]
	s_waitcnt vmcnt(11)
	v_cvt_pk_bf16_f32 v36, v36, v37
	v_cvt_pk_bf16_f32 v37, v38, v39
	v_cvt_pk_bf16_f32 v38, v40, v41
	v_cvt_pk_bf16_f32 v39, v42, v43
	global_store_dwordx4 v[0:1], v[36:39], off
	v_lshl_add_u64 v[0:1], v[0:1], 0, s[8:9]
	s_waitcnt vmcnt(10)
	v_cvt_pk_bf16_f32 v44, v44, v45
	v_cvt_pk_bf16_f32 v45, v46, v47
	v_cvt_pk_bf16_f32 v46, v48, v49
	v_cvt_pk_bf16_f32 v47, v50, v51
	global_store_dwordx4 v[0:1], v[44:47], off
	v_lshl_add_u64 v[0:1], v[0:1], 0, s[8:9]
	s_waitcnt vmcnt(9)
	v_cvt_pk_bf16_f32 v52, v52, v53
	v_cvt_pk_bf16_f32 v53, v54, v55
	v_cvt_pk_bf16_f32 v54, v56, v57
	v_cvt_pk_bf16_f32 v55, v58, v59
	global_store_dwordx4 v[0:1], v[52:55], off
	v_lshl_add_u64 v[0:1], v[0:1], 0, s[8:9]
	s_waitcnt vmcnt(8)
	v_cvt_pk_bf16_f32 v60, v60, v61
	v_cvt_pk_bf16_f32 v61, v62, v63
	v_cvt_pk_bf16_f32 v62, v64, v65
	v_cvt_pk_bf16_f32 v63, v66, v67
	global_store_dwordx4 v[0:1], v[60:63], off
	v_lshl_add_u64 v[0:1], v[0:1], 0, s[8:9]
	s_waitcnt vmcnt(7)
	v_cvt_pk_bf16_f32 v68, v68, v69
	v_cvt_pk_bf16_f32 v69, v70, v71
	v_cvt_pk_bf16_f32 v70, v72, v73
	v_cvt_pk_bf16_f32 v71, v74, v75
	global_store_dwordx4 v[0:1], v[68:71], off
	v_lshl_add_u64 v[0:1], v[0:1], 0, s[8:9]
	s_lshl_b32 s31, s54, 3
	s_add_i32 s3, s3, s31
	s_cmpk_lt_i32 s3, 0x4000
	s_cbranch_scc1 .LBB0_139
	s_branch .LBB0_140
